# P10 block selection: eight queries of a wave ranked together (32 candidates per lane, 13 threshold rounds, exact fallback to the original loop on ties); dead pre-loop work removed; full blocks' tasks
# speedup vs baseline: 1.1324x; 1.0199x over previous
.LBB0_1265:
	s_sub_i32 s54, 0x1ff, s12
	s_ashr_i32 s53, s54, 1
	s_mov_b32 s99, s53
	s_cmp_gt_i32 s53, 15
	s_cbranch_scc0 .Ltk8_noearly
	v_lshrrev_b32_e32 v134, 3, v199
	v_and_b32_e32 v135, 7, v199
	s_lshl_b32 s66, s53, 6
	s_add_i32 s66, s66, s34
	s_and_b32 s67, s54, 1
	v_add_u32_e32 v136, s66, v134
	v_lshlrev_b32_e32 v136, 1, v136
	v_or_b32_e32 v136, s67, v136
	v_lshlrev_b32_e32 v136, 10, v136
	v_lshl_add_u32 v136, v135, 7, v136
	s_add_u32 s64, s72, 0xba00000
	s_addc_u32 s65, s73, 0
	global_load_dwordx4 v[102:105], v136, s[64:65]
	global_load_dwordx4 v[106:109], v136, s[64:65] offset:16
	global_load_dwordx4 v[110:113], v136, s[64:65] offset:32
	global_load_dwordx4 v[114:117], v136, s[64:65] offset:48
	global_load_dwordx4 v[118:121], v136, s[64:65] offset:64
	global_load_dwordx4 v[122:125], v136, s[64:65] offset:80
	global_load_dwordx4 v[126:129], v136, s[64:65] offset:96
	global_load_dwordx4 v[130:133], v136, s[64:65] offset:112
.Ltk8_noearly:
	s_cmp_gt_i32 s53, 15
	s_mov_b64 s[0:1], -1
	ds_write_b32 v203, v3
	s_waitcnt lgkmcnt(0)
	s_barrier
	s_cbranch_scc0 .LBB0_1297
	s_and_saveexec_b64 s[0:1], s[2:3]
	s_cbranch_execz .LBB0_1268
	v_readlane_b32 s8, v254, 5
	v_add_lshl_u32 v2, s53, v207, 1
	v_readlane_b32 s9, v254, 6
	s_nop 1
	v_cndmask_b32_e64 v2, v2, 0, s[8:9]
	v_lshl_add_u32 v2, v2, 2, 0
	ds_write_b64 v2, v[212:213]
.LBB0_1268:
	s_or_b64 exec, exec, s[0:1]
	v_lshlrev_b32_e32 v137, 5, v135
	v_add_u32_e32 v138, -1, v137
	s_add_i32 s10, s53, -2
	v_lshl_add_u32 v139, v135, 8, s35
	v_add_u32_e32 v140, s46, v134
	v_lshlrev_b32_e64 v140, v140, 1
	s_waitcnt vmcnt(0)
	v_add_u32_e32 v102, 1, v102
	v_add_u32_e32 v145, 0, v138
	v_cmp_gt_u32_e32 vcc, s10, v145
	v_cndmask_b32_e32 v102, 0, v102, vcc
	v_add_u32_e32 v103, 1, v103
	v_add_u32_e32 v145, 1, v138
	v_cmp_gt_u32_e32 vcc, s10, v145
	v_cndmask_b32_e32 v103, 0, v103, vcc
	v_add_u32_e32 v104, 1, v104
	v_add_u32_e32 v145, 2, v138
	v_cmp_gt_u32_e32 vcc, s10, v145
	v_cndmask_b32_e32 v104, 0, v104, vcc
	v_add_u32_e32 v105, 1, v105
	v_add_u32_e32 v145, 3, v138
	v_cmp_gt_u32_e32 vcc, s10, v145
	v_cndmask_b32_e32 v105, 0, v105, vcc
	v_add_u32_e32 v106, 1, v106
	v_add_u32_e32 v145, 4, v138
	v_cmp_gt_u32_e32 vcc, s10, v145
	v_cndmask_b32_e32 v106, 0, v106, vcc
	v_add_u32_e32 v107, 1, v107
	v_add_u32_e32 v145, 5, v138
	v_cmp_gt_u32_e32 vcc, s10, v145
	v_cndmask_b32_e32 v107, 0, v107, vcc
	v_add_u32_e32 v108, 1, v108
	v_add_u32_e32 v145, 6, v138
	v_cmp_gt_u32_e32 vcc, s10, v145
	v_cndmask_b32_e32 v108, 0, v108, vcc
	v_add_u32_e32 v109, 1, v109
	v_add_u32_e32 v145, 7, v138
	v_cmp_gt_u32_e32 vcc, s10, v145
	v_cndmask_b32_e32 v109, 0, v109, vcc
	v_add_u32_e32 v110, 1, v110
	v_add_u32_e32 v145, 8, v138
	v_cmp_gt_u32_e32 vcc, s10, v145
	v_cndmask_b32_e32 v110, 0, v110, vcc
	v_add_u32_e32 v111, 1, v111
	v_add_u32_e32 v145, 9, v138
	v_cmp_gt_u32_e32 vcc, s10, v145
	v_cndmask_b32_e32 v111, 0, v111, vcc
	v_add_u32_e32 v112, 1, v112
	v_add_u32_e32 v145, 10, v138
	v_cmp_gt_u32_e32 vcc, s10, v145
	v_cndmask_b32_e32 v112, 0, v112, vcc
	v_add_u32_e32 v113, 1, v113
	v_add_u32_e32 v145, 11, v138
	v_cmp_gt_u32_e32 vcc, s10, v145
	v_cndmask_b32_e32 v113, 0, v113, vcc
	v_add_u32_e32 v114, 1, v114
	v_add_u32_e32 v145, 12, v138
	v_cmp_gt_u32_e32 vcc, s10, v145
	v_cndmask_b32_e32 v114, 0, v114, vcc
	v_add_u32_e32 v115, 1, v115
	v_add_u32_e32 v145, 13, v138
	v_cmp_gt_u32_e32 vcc, s10, v145
	v_cndmask_b32_e32 v115, 0, v115, vcc
	v_add_u32_e32 v116, 1, v116
	v_add_u32_e32 v145, 14, v138
	v_cmp_gt_u32_e32 vcc, s10, v145
	v_cndmask_b32_e32 v116, 0, v116, vcc
	v_add_u32_e32 v117, 1, v117
	v_add_u32_e32 v145, 15, v138
	v_cmp_gt_u32_e32 vcc, s10, v145
	v_cndmask_b32_e32 v117, 0, v117, vcc
	v_add_u32_e32 v118, 1, v118
	v_add_u32_e32 v145, 16, v138
	v_cmp_gt_u32_e32 vcc, s10, v145
	v_cndmask_b32_e32 v118, 0, v118, vcc
	v_add_u32_e32 v119, 1, v119
	v_add_u32_e32 v145, 17, v138
	v_cmp_gt_u32_e32 vcc, s10, v145
	v_cndmask_b32_e32 v119, 0, v119, vcc
	v_add_u32_e32 v120, 1, v120
	v_add_u32_e32 v145, 18, v138
	v_cmp_gt_u32_e32 vcc, s10, v145
	v_cndmask_b32_e32 v120, 0, v120, vcc
	v_add_u32_e32 v121, 1, v121
	v_add_u32_e32 v145, 19, v138
	v_cmp_gt_u32_e32 vcc, s10, v145
	v_cndmask_b32_e32 v121, 0, v121, vcc
	v_add_u32_e32 v122, 1, v122
	v_add_u32_e32 v145, 20, v138
	v_cmp_gt_u32_e32 vcc, s10, v145
	v_cndmask_b32_e32 v122, 0, v122, vcc
	v_add_u32_e32 v123, 1, v123
	v_add_u32_e32 v145, 21, v138
	v_cmp_gt_u32_e32 vcc, s10, v145
	v_cndmask_b32_e32 v123, 0, v123, vcc
	v_add_u32_e32 v124, 1, v124
	v_add_u32_e32 v145, 22, v138
	v_cmp_gt_u32_e32 vcc, s10, v145
	v_cndmask_b32_e32 v124, 0, v124, vcc
	v_add_u32_e32 v125, 1, v125
	v_add_u32_e32 v145, 23, v138
	v_cmp_gt_u32_e32 vcc, s10, v145
	v_cndmask_b32_e32 v125, 0, v125, vcc
	v_add_u32_e32 v126, 1, v126
	v_add_u32_e32 v145, 24, v138
	v_cmp_gt_u32_e32 vcc, s10, v145
	v_cndmask_b32_e32 v126, 0, v126, vcc
	v_add_u32_e32 v127, 1, v127
	v_add_u32_e32 v145, 25, v138
	v_cmp_gt_u32_e32 vcc, s10, v145
	v_cndmask_b32_e32 v127, 0, v127, vcc
	v_add_u32_e32 v128, 1, v128
	v_add_u32_e32 v145, 26, v138
	v_cmp_gt_u32_e32 vcc, s10, v145
	v_cndmask_b32_e32 v128, 0, v128, vcc
	v_add_u32_e32 v129, 1, v129
	v_add_u32_e32 v145, 27, v138
	v_cmp_gt_u32_e32 vcc, s10, v145
	v_cndmask_b32_e32 v129, 0, v129, vcc
	v_add_u32_e32 v130, 1, v130
	v_add_u32_e32 v145, 28, v138
	v_cmp_gt_u32_e32 vcc, s10, v145
	v_cndmask_b32_e32 v130, 0, v130, vcc
	v_add_u32_e32 v131, 1, v131
	v_add_u32_e32 v145, 29, v138
	v_cmp_gt_u32_e32 vcc, s10, v145
	v_cndmask_b32_e32 v131, 0, v131, vcc
	v_add_u32_e32 v132, 1, v132
	v_add_u32_e32 v145, 30, v138
	v_cmp_gt_u32_e32 vcc, s10, v145
	v_cndmask_b32_e32 v132, 0, v132, vcc
	v_add_u32_e32 v133, 1, v133
	v_add_u32_e32 v145, 31, v138
	v_cmp_gt_u32_e32 vcc, s10, v145
	v_cndmask_b32_e32 v133, 0, v133, vcc
	v_mov_b32_e32 v141, -1
	v_sub_u32_e32 v142, v141, v102
	v_sub_u32_e32 v145, v141, v103
	v_min_u32_e32 v142, v142, v145
	v_sub_u32_e32 v145, v141, v104
	v_sub_u32_e32 v146, v141, v105
	v_min3_u32 v142, v142, v145, v146
	v_sub_u32_e32 v145, v141, v106
	v_sub_u32_e32 v146, v141, v107
	v_min3_u32 v142, v142, v145, v146
	v_sub_u32_e32 v145, v141, v108
	v_sub_u32_e32 v146, v141, v109
	v_min3_u32 v142, v142, v145, v146
	v_sub_u32_e32 v145, v141, v110
	v_sub_u32_e32 v146, v141, v111
	v_min3_u32 v142, v142, v145, v146
	v_sub_u32_e32 v145, v141, v112
	v_sub_u32_e32 v146, v141, v113
	v_min3_u32 v142, v142, v145, v146
	v_sub_u32_e32 v145, v141, v114
	v_sub_u32_e32 v146, v141, v115
	v_min3_u32 v142, v142, v145, v146
	v_sub_u32_e32 v145, v141, v116
	v_sub_u32_e32 v146, v141, v117
	v_min3_u32 v142, v142, v145, v146
	v_sub_u32_e32 v145, v141, v118
	v_sub_u32_e32 v146, v141, v119
	v_min3_u32 v142, v142, v145, v146
	v_sub_u32_e32 v145, v141, v120
	v_sub_u32_e32 v146, v141, v121
	v_min3_u32 v142, v142, v145, v146
	v_sub_u32_e32 v145, v141, v122
	v_sub_u32_e32 v146, v141, v123
	v_min3_u32 v142, v142, v145, v146
	v_sub_u32_e32 v145, v141, v124
	v_sub_u32_e32 v146, v141, v125
	v_min3_u32 v142, v142, v145, v146
	v_sub_u32_e32 v145, v141, v126
	v_sub_u32_e32 v146, v141, v127
	v_min3_u32 v142, v142, v145, v146
	v_sub_u32_e32 v145, v141, v128
	v_sub_u32_e32 v146, v141, v129
	v_min3_u32 v142, v142, v145, v146
	v_sub_u32_e32 v145, v141, v130
	v_sub_u32_e32 v146, v141, v131
	v_min3_u32 v142, v142, v145, v146
	v_sub_u32_e32 v145, v141, v132
	v_sub_u32_e32 v146, v141, v133
	v_min3_u32 v142, v142, v145, v146
	s_nop 1
	v_min_u32_dpp v142, v142, v142 quad_perm:[1,0,3,2] row_mask:0xf bank_mask:0xf
	s_nop 1
	v_min_u32_dpp v142, v142, v142 quad_perm:[2,3,0,1] row_mask:0xf bank_mask:0xf
	s_nop 1
	v_min_u32_dpp v142, v142, v142 row_half_mirror row_mask:0xf bank_mask:0xf
	v_sub_u32_e32 v143, v141, v142
	v_add_u32_e32 v141, -1, v143
	v_sub_u32_e32 v142, v141, v102
	v_sub_u32_e32 v145, v141, v103
	v_min_u32_e32 v142, v142, v145
	v_sub_u32_e32 v145, v141, v104
	v_sub_u32_e32 v146, v141, v105
	v_min3_u32 v142, v142, v145, v146
	v_sub_u32_e32 v145, v141, v106
	v_sub_u32_e32 v146, v141, v107
	v_min3_u32 v142, v142, v145, v146
	v_sub_u32_e32 v145, v141, v108
	v_sub_u32_e32 v146, v141, v109
	v_min3_u32 v142, v142, v145, v146
	v_sub_u32_e32 v145, v141, v110
	v_sub_u32_e32 v146, v141, v111
	v_min3_u32 v142, v142, v145, v146
	v_sub_u32_e32 v145, v141, v112
	v_sub_u32_e32 v146, v141, v113
	v_min3_u32 v142, v142, v145, v146
	v_sub_u32_e32 v145, v141, v114
	v_sub_u32_e32 v146, v141, v115
	v_min3_u32 v142, v142, v145, v146
	v_sub_u32_e32 v145, v141, v116
	v_sub_u32_e32 v146, v141, v117
	v_min3_u32 v142, v142, v145, v146
	v_sub_u32_e32 v145, v141, v118
	v_sub_u32_e32 v146, v141, v119
	v_min3_u32 v142, v142, v145, v146
	v_sub_u32_e32 v145, v141, v120
	v_sub_u32_e32 v146, v141, v121
	v_min3_u32 v142, v142, v145, v146
	v_sub_u32_e32 v145, v141, v122
	v_sub_u32_e32 v146, v141, v123
	v_min3_u32 v142, v142, v145, v146
	v_sub_u32_e32 v145, v141, v124
	v_sub_u32_e32 v146, v141, v125
	v_min3_u32 v142, v142, v145, v146
	v_sub_u32_e32 v145, v141, v126
	v_sub_u32_e32 v146, v141, v127
	v_min3_u32 v142, v142, v145, v146
	v_sub_u32_e32 v145, v141, v128
	v_sub_u32_e32 v146, v141, v129
	v_min3_u32 v142, v142, v145, v146
	v_sub_u32_e32 v145, v141, v130
	v_sub_u32_e32 v146, v141, v131
	v_min3_u32 v142, v142, v145, v146
	v_sub_u32_e32 v145, v141, v132
	v_sub_u32_e32 v146, v141, v133
	v_min3_u32 v142, v142, v145, v146
	s_nop 1
	v_min_u32_dpp v142, v142, v142 quad_perm:[1,0,3,2] row_mask:0xf bank_mask:0xf
	s_nop 1
	v_min_u32_dpp v142, v142, v142 quad_perm:[2,3,0,1] row_mask:0xf bank_mask:0xf
	s_nop 1
	v_min_u32_dpp v142, v142, v142 row_half_mirror row_mask:0xf bank_mask:0xf
	v_sub_u32_e32 v143, v141, v142
	v_add_u32_e32 v141, -1, v143
	v_sub_u32_e32 v142, v141, v102
	v_sub_u32_e32 v145, v141, v103
	v_min_u32_e32 v142, v142, v145
	v_sub_u32_e32 v145, v141, v104
	v_sub_u32_e32 v146, v141, v105
	v_min3_u32 v142, v142, v145, v146
	v_sub_u32_e32 v145, v141, v106
	v_sub_u32_e32 v146, v141, v107
	v_min3_u32 v142, v142, v145, v146
	v_sub_u32_e32 v145, v141, v108
	v_sub_u32_e32 v146, v141, v109
	v_min3_u32 v142, v142, v145, v146
	v_sub_u32_e32 v145, v141, v110
	v_sub_u32_e32 v146, v141, v111
	v_min3_u32 v142, v142, v145, v146
	v_sub_u32_e32 v145, v141, v112
	v_sub_u32_e32 v146, v141, v113
	v_min3_u32 v142, v142, v145, v146
	v_sub_u32_e32 v145, v141, v114
	v_sub_u32_e32 v146, v141, v115
	v_min3_u32 v142, v142, v145, v146
	v_sub_u32_e32 v145, v141, v116
	v_sub_u32_e32 v146, v141, v117
	v_min3_u32 v142, v142, v145, v146
	v_sub_u32_e32 v145, v141, v118
	v_sub_u32_e32 v146, v141, v119
	v_min3_u32 v142, v142, v145, v146
	v_sub_u32_e32 v145, v141, v120
	v_sub_u32_e32 v146, v141, v121
	v_min3_u32 v142, v142, v145, v146
	v_sub_u32_e32 v145, v141, v122
	v_sub_u32_e32 v146, v141, v123
	v_min3_u32 v142, v142, v145, v146
	v_sub_u32_e32 v145, v141, v124
	v_sub_u32_e32 v146, v141, v125
	v_min3_u32 v142, v142, v145, v146
	v_sub_u32_e32 v145, v141, v126
	v_sub_u32_e32 v146, v141, v127
	v_min3_u32 v142, v142, v145, v146
	v_sub_u32_e32 v145, v141, v128
	v_sub_u32_e32 v146, v141, v129
	v_min3_u32 v142, v142, v145, v146
	v_sub_u32_e32 v145, v141, v130
	v_sub_u32_e32 v146, v141, v131
	v_min3_u32 v142, v142, v145, v146
	v_sub_u32_e32 v145, v141, v132
	v_sub_u32_e32 v146, v141, v133
	v_min3_u32 v142, v142, v145, v146
	s_nop 1
	v_min_u32_dpp v142, v142, v142 quad_perm:[1,0,3,2] row_mask:0xf bank_mask:0xf
	s_nop 1
	v_min_u32_dpp v142, v142, v142 quad_perm:[2,3,0,1] row_mask:0xf bank_mask:0xf
	s_nop 1
	v_min_u32_dpp v142, v142, v142 row_half_mirror row_mask:0xf bank_mask:0xf
	v_sub_u32_e32 v143, v141, v142
	v_add_u32_e32 v141, -1, v143
	v_sub_u32_e32 v142, v141, v102
	v_sub_u32_e32 v145, v141, v103
	v_min_u32_e32 v142, v142, v145
	v_sub_u32_e32 v145, v141, v104
	v_sub_u32_e32 v146, v141, v105
	v_min3_u32 v142, v142, v145, v146
	v_sub_u32_e32 v145, v141, v106
	v_sub_u32_e32 v146, v141, v107
	v_min3_u32 v142, v142, v145, v146
	v_sub_u32_e32 v145, v141, v108
	v_sub_u32_e32 v146, v141, v109
	v_min3_u32 v142, v142, v145, v146
	v_sub_u32_e32 v145, v141, v110
	v_sub_u32_e32 v146, v141, v111
	v_min3_u32 v142, v142, v145, v146
	v_sub_u32_e32 v145, v141, v112
	v_sub_u32_e32 v146, v141, v113
	v_min3_u32 v142, v142, v145, v146
	v_sub_u32_e32 v145, v141, v114
	v_sub_u32_e32 v146, v141, v115
	v_min3_u32 v142, v142, v145, v146
	v_sub_u32_e32 v145, v141, v116
	v_sub_u32_e32 v146, v141, v117
	v_min3_u32 v142, v142, v145, v146
	v_sub_u32_e32 v145, v141, v118
	v_sub_u32_e32 v146, v141, v119
	v_min3_u32 v142, v142, v145, v146
	v_sub_u32_e32 v145, v141, v120
	v_sub_u32_e32 v146, v141, v121
	v_min3_u32 v142, v142, v145, v146
	v_sub_u32_e32 v145, v141, v122
	v_sub_u32_e32 v146, v141, v123
	v_min3_u32 v142, v142, v145, v146
	v_sub_u32_e32 v145, v141, v124
	v_sub_u32_e32 v146, v141, v125
	v_min3_u32 v142, v142, v145, v146
	v_sub_u32_e32 v145, v141, v126
	v_sub_u32_e32 v146, v141, v127
	v_min3_u32 v142, v142, v145, v146
	v_sub_u32_e32 v145, v141, v128
	v_sub_u32_e32 v146, v141, v129
	v_min3_u32 v142, v142, v145, v146
	v_sub_u32_e32 v145, v141, v130
	v_sub_u32_e32 v146, v141, v131
	v_min3_u32 v142, v142, v145, v146
	v_sub_u32_e32 v145, v141, v132
	v_sub_u32_e32 v146, v141, v133
	v_min3_u32 v142, v142, v145, v146
	s_nop 1
	v_min_u32_dpp v142, v142, v142 quad_perm:[1,0,3,2] row_mask:0xf bank_mask:0xf
	s_nop 1
	v_min_u32_dpp v142, v142, v142 quad_perm:[2,3,0,1] row_mask:0xf bank_mask:0xf
	s_nop 1
	v_min_u32_dpp v142, v142, v142 row_half_mirror row_mask:0xf bank_mask:0xf
	v_sub_u32_e32 v143, v141, v142
	v_add_u32_e32 v141, -1, v143
	v_sub_u32_e32 v142, v141, v102
	v_sub_u32_e32 v145, v141, v103
	v_min_u32_e32 v142, v142, v145
	v_sub_u32_e32 v145, v141, v104
	v_sub_u32_e32 v146, v141, v105
	v_min3_u32 v142, v142, v145, v146
	v_sub_u32_e32 v145, v141, v106
	v_sub_u32_e32 v146, v141, v107
	v_min3_u32 v142, v142, v145, v146
	v_sub_u32_e32 v145, v141, v108
	v_sub_u32_e32 v146, v141, v109
	v_min3_u32 v142, v142, v145, v146
	v_sub_u32_e32 v145, v141, v110
	v_sub_u32_e32 v146, v141, v111
	v_min3_u32 v142, v142, v145, v146
	v_sub_u32_e32 v145, v141, v112
	v_sub_u32_e32 v146, v141, v113
	v_min3_u32 v142, v142, v145, v146
	v_sub_u32_e32 v145, v141, v114
	v_sub_u32_e32 v146, v141, v115
	v_min3_u32 v142, v142, v145, v146
	v_sub_u32_e32 v145, v141, v116
	v_sub_u32_e32 v146, v141, v117
	v_min3_u32 v142, v142, v145, v146
	v_sub_u32_e32 v145, v141, v118
	v_sub_u32_e32 v146, v141, v119
	v_min3_u32 v142, v142, v145, v146
	v_sub_u32_e32 v145, v141, v120
	v_sub_u32_e32 v146, v141, v121
	v_min3_u32 v142, v142, v145, v146
	v_sub_u32_e32 v145, v141, v122
	v_sub_u32_e32 v146, v141, v123
	v_min3_u32 v142, v142, v145, v146
	v_sub_u32_e32 v145, v141, v124
	v_sub_u32_e32 v146, v141, v125
	v_min3_u32 v142, v142, v145, v146
	v_sub_u32_e32 v145, v141, v126
	v_sub_u32_e32 v146, v141, v127
	v_min3_u32 v142, v142, v145, v146
	v_sub_u32_e32 v145, v141, v128
	v_sub_u32_e32 v146, v141, v129
	v_min3_u32 v142, v142, v145, v146
	v_sub_u32_e32 v145, v141, v130
	v_sub_u32_e32 v146, v141, v131
	v_min3_u32 v142, v142, v145, v146
	v_sub_u32_e32 v145, v141, v132
	v_sub_u32_e32 v146, v141, v133
	v_min3_u32 v142, v142, v145, v146
	s_nop 1
	v_min_u32_dpp v142, v142, v142 quad_perm:[1,0,3,2] row_mask:0xf bank_mask:0xf
	s_nop 1
	v_min_u32_dpp v142, v142, v142 quad_perm:[2,3,0,1] row_mask:0xf bank_mask:0xf
	s_nop 1
	v_min_u32_dpp v142, v142, v142 row_half_mirror row_mask:0xf bank_mask:0xf
	v_sub_u32_e32 v143, v141, v142
	v_add_u32_e32 v141, -1, v143
	v_sub_u32_e32 v142, v141, v102
	v_sub_u32_e32 v145, v141, v103
	v_min_u32_e32 v142, v142, v145
	v_sub_u32_e32 v145, v141, v104
	v_sub_u32_e32 v146, v141, v105
	v_min3_u32 v142, v142, v145, v146
	v_sub_u32_e32 v145, v141, v106
	v_sub_u32_e32 v146, v141, v107
	v_min3_u32 v142, v142, v145, v146
	v_sub_u32_e32 v145, v141, v108
	v_sub_u32_e32 v146, v141, v109
	v_min3_u32 v142, v142, v145, v146
	v_sub_u32_e32 v145, v141, v110
	v_sub_u32_e32 v146, v141, v111
	v_min3_u32 v142, v142, v145, v146
	v_sub_u32_e32 v145, v141, v112
	v_sub_u32_e32 v146, v141, v113
	v_min3_u32 v142, v142, v145, v146
	v_sub_u32_e32 v145, v141, v114
	v_sub_u32_e32 v146, v141, v115
	v_min3_u32 v142, v142, v145, v146
	v_sub_u32_e32 v145, v141, v116
	v_sub_u32_e32 v146, v141, v117
	v_min3_u32 v142, v142, v145, v146
	v_sub_u32_e32 v145, v141, v118
	v_sub_u32_e32 v146, v141, v119
	v_min3_u32 v142, v142, v145, v146
	v_sub_u32_e32 v145, v141, v120
	v_sub_u32_e32 v146, v141, v121
	v_min3_u32 v142, v142, v145, v146
	v_sub_u32_e32 v145, v141, v122
	v_sub_u32_e32 v146, v141, v123
	v_min3_u32 v142, v142, v145, v146
	v_sub_u32_e32 v145, v141, v124
	v_sub_u32_e32 v146, v141, v125
	v_min3_u32 v142, v142, v145, v146
	v_sub_u32_e32 v145, v141, v126
	v_sub_u32_e32 v146, v141, v127
	v_min3_u32 v142, v142, v145, v146
	v_sub_u32_e32 v145, v141, v128
	v_sub_u32_e32 v146, v141, v129
	v_min3_u32 v142, v142, v145, v146
	v_sub_u32_e32 v145, v141, v130
	v_sub_u32_e32 v146, v141, v131
	v_min3_u32 v142, v142, v145, v146
	v_sub_u32_e32 v145, v141, v132
	v_sub_u32_e32 v146, v141, v133
	v_min3_u32 v142, v142, v145, v146
	s_nop 1
	v_min_u32_dpp v142, v142, v142 quad_perm:[1,0,3,2] row_mask:0xf bank_mask:0xf
	s_nop 1
	v_min_u32_dpp v142, v142, v142 quad_perm:[2,3,0,1] row_mask:0xf bank_mask:0xf
	s_nop 1
	v_min_u32_dpp v142, v142, v142 row_half_mirror row_mask:0xf bank_mask:0xf
	v_sub_u32_e32 v143, v141, v142
	v_add_u32_e32 v141, -1, v143
	v_sub_u32_e32 v142, v141, v102
	v_sub_u32_e32 v145, v141, v103
	v_min_u32_e32 v142, v142, v145
	v_sub_u32_e32 v145, v141, v104
	v_sub_u32_e32 v146, v141, v105
	v_min3_u32 v142, v142, v145, v146
	v_sub_u32_e32 v145, v141, v106
	v_sub_u32_e32 v146, v141, v107
	v_min3_u32 v142, v142, v145, v146
	v_sub_u32_e32 v145, v141, v108
	v_sub_u32_e32 v146, v141, v109
	v_min3_u32 v142, v142, v145, v146
	v_sub_u32_e32 v145, v141, v110
	v_sub_u32_e32 v146, v141, v111
	v_min3_u32 v142, v142, v145, v146
	v_sub_u32_e32 v145, v141, v112
	v_sub_u32_e32 v146, v141, v113
	v_min3_u32 v142, v142, v145, v146
	v_sub_u32_e32 v145, v141, v114
	v_sub_u32_e32 v146, v141, v115
	v_min3_u32 v142, v142, v145, v146
	v_sub_u32_e32 v145, v141, v116
	v_sub_u32_e32 v146, v141, v117
	v_min3_u32 v142, v142, v145, v146
	v_sub_u32_e32 v145, v141, v118
	v_sub_u32_e32 v146, v141, v119
	v_min3_u32 v142, v142, v145, v146
	v_sub_u32_e32 v145, v141, v120
	v_sub_u32_e32 v146, v141, v121
	v_min3_u32 v142, v142, v145, v146
	v_sub_u32_e32 v145, v141, v122
	v_sub_u32_e32 v146, v141, v123
	v_min3_u32 v142, v142, v145, v146
	v_sub_u32_e32 v145, v141, v124
	v_sub_u32_e32 v146, v141, v125
	v_min3_u32 v142, v142, v145, v146
	v_sub_u32_e32 v145, v141, v126
	v_sub_u32_e32 v146, v141, v127
	v_min3_u32 v142, v142, v145, v146
	v_sub_u32_e32 v145, v141, v128
	v_sub_u32_e32 v146, v141, v129
	v_min3_u32 v142, v142, v145, v146
	v_sub_u32_e32 v145, v141, v130
	v_sub_u32_e32 v146, v141, v131
	v_min3_u32 v142, v142, v145, v146
	v_sub_u32_e32 v145, v141, v132
	v_sub_u32_e32 v146, v141, v133
	v_min3_u32 v142, v142, v145, v146
	s_nop 1
	v_min_u32_dpp v142, v142, v142 quad_perm:[1,0,3,2] row_mask:0xf bank_mask:0xf
	s_nop 1
	v_min_u32_dpp v142, v142, v142 quad_perm:[2,3,0,1] row_mask:0xf bank_mask:0xf
	s_nop 1
	v_min_u32_dpp v142, v142, v142 row_half_mirror row_mask:0xf bank_mask:0xf
	v_sub_u32_e32 v143, v141, v142
	v_add_u32_e32 v141, -1, v143
	v_sub_u32_e32 v142, v141, v102
	v_sub_u32_e32 v145, v141, v103
	v_min_u32_e32 v142, v142, v145
	v_sub_u32_e32 v145, v141, v104
	v_sub_u32_e32 v146, v141, v105
	v_min3_u32 v142, v142, v145, v146
	v_sub_u32_e32 v145, v141, v106
	v_sub_u32_e32 v146, v141, v107
	v_min3_u32 v142, v142, v145, v146
	v_sub_u32_e32 v145, v141, v108
	v_sub_u32_e32 v146, v141, v109
	v_min3_u32 v142, v142, v145, v146
	v_sub_u32_e32 v145, v141, v110
	v_sub_u32_e32 v146, v141, v111
	v_min3_u32 v142, v142, v145, v146
	v_sub_u32_e32 v145, v141, v112
	v_sub_u32_e32 v146, v141, v113
	v_min3_u32 v142, v142, v145, v146
	v_sub_u32_e32 v145, v141, v114
	v_sub_u32_e32 v146, v141, v115
	v_min3_u32 v142, v142, v145, v146
	v_sub_u32_e32 v145, v141, v116
	v_sub_u32_e32 v146, v141, v117
	v_min3_u32 v142, v142, v145, v146
	v_sub_u32_e32 v145, v141, v118
	v_sub_u32_e32 v146, v141, v119
	v_min3_u32 v142, v142, v145, v146
	v_sub_u32_e32 v145, v141, v120
	v_sub_u32_e32 v146, v141, v121
	v_min3_u32 v142, v142, v145, v146
	v_sub_u32_e32 v145, v141, v122
	v_sub_u32_e32 v146, v141, v123
	v_min3_u32 v142, v142, v145, v146
	v_sub_u32_e32 v145, v141, v124
	v_sub_u32_e32 v146, v141, v125
	v_min3_u32 v142, v142, v145, v146
	v_sub_u32_e32 v145, v141, v126
	v_sub_u32_e32 v146, v141, v127
	v_min3_u32 v142, v142, v145, v146
	v_sub_u32_e32 v145, v141, v128
	v_sub_u32_e32 v146, v141, v129
	v_min3_u32 v142, v142, v145, v146
	v_sub_u32_e32 v145, v141, v130
	v_sub_u32_e32 v146, v141, v131
	v_min3_u32 v142, v142, v145, v146
	v_sub_u32_e32 v145, v141, v132
	v_sub_u32_e32 v146, v141, v133
	v_min3_u32 v142, v142, v145, v146
	s_nop 1
	v_min_u32_dpp v142, v142, v142 quad_perm:[1,0,3,2] row_mask:0xf bank_mask:0xf
	s_nop 1
	v_min_u32_dpp v142, v142, v142 quad_perm:[2,3,0,1] row_mask:0xf bank_mask:0xf
	s_nop 1
	v_min_u32_dpp v142, v142, v142 row_half_mirror row_mask:0xf bank_mask:0xf
	v_sub_u32_e32 v143, v141, v142
	v_add_u32_e32 v141, -1, v143
	v_sub_u32_e32 v142, v141, v102
	v_sub_u32_e32 v145, v141, v103
	v_min_u32_e32 v142, v142, v145
	v_sub_u32_e32 v145, v141, v104
	v_sub_u32_e32 v146, v141, v105
	v_min3_u32 v142, v142, v145, v146
	v_sub_u32_e32 v145, v141, v106
	v_sub_u32_e32 v146, v141, v107
	v_min3_u32 v142, v142, v145, v146
	v_sub_u32_e32 v145, v141, v108
	v_sub_u32_e32 v146, v141, v109
	v_min3_u32 v142, v142, v145, v146
	v_sub_u32_e32 v145, v141, v110
	v_sub_u32_e32 v146, v141, v111
	v_min3_u32 v142, v142, v145, v146
	v_sub_u32_e32 v145, v141, v112
	v_sub_u32_e32 v146, v141, v113
	v_min3_u32 v142, v142, v145, v146
	v_sub_u32_e32 v145, v141, v114
	v_sub_u32_e32 v146, v141, v115
	v_min3_u32 v142, v142, v145, v146
	v_sub_u32_e32 v145, v141, v116
	v_sub_u32_e32 v146, v141, v117
	v_min3_u32 v142, v142, v145, v146
	v_sub_u32_e32 v145, v141, v118
	v_sub_u32_e32 v146, v141, v119
	v_min3_u32 v142, v142, v145, v146
	v_sub_u32_e32 v145, v141, v120
	v_sub_u32_e32 v146, v141, v121
	v_min3_u32 v142, v142, v145, v146
	v_sub_u32_e32 v145, v141, v122
	v_sub_u32_e32 v146, v141, v123
	v_min3_u32 v142, v142, v145, v146
	v_sub_u32_e32 v145, v141, v124
	v_sub_u32_e32 v146, v141, v125
	v_min3_u32 v142, v142, v145, v146
	v_sub_u32_e32 v145, v141, v126
	v_sub_u32_e32 v146, v141, v127
	v_min3_u32 v142, v142, v145, v146
	v_sub_u32_e32 v145, v141, v128
	v_sub_u32_e32 v146, v141, v129
	v_min3_u32 v142, v142, v145, v146
	v_sub_u32_e32 v145, v141, v130
	v_sub_u32_e32 v146, v141, v131
	v_min3_u32 v142, v142, v145, v146
	v_sub_u32_e32 v145, v141, v132
	v_sub_u32_e32 v146, v141, v133
	v_min3_u32 v142, v142, v145, v146
	s_nop 1
	v_min_u32_dpp v142, v142, v142 quad_perm:[1,0,3,2] row_mask:0xf bank_mask:0xf
	s_nop 1
	v_min_u32_dpp v142, v142, v142 quad_perm:[2,3,0,1] row_mask:0xf bank_mask:0xf
	s_nop 1
	v_min_u32_dpp v142, v142, v142 row_half_mirror row_mask:0xf bank_mask:0xf
	v_sub_u32_e32 v143, v141, v142
	v_add_u32_e32 v141, -1, v143
	v_sub_u32_e32 v142, v141, v102
	v_sub_u32_e32 v145, v141, v103
	v_min_u32_e32 v142, v142, v145
	v_sub_u32_e32 v145, v141, v104
	v_sub_u32_e32 v146, v141, v105
	v_min3_u32 v142, v142, v145, v146
	v_sub_u32_e32 v145, v141, v106
	v_sub_u32_e32 v146, v141, v107
	v_min3_u32 v142, v142, v145, v146
	v_sub_u32_e32 v145, v141, v108
	v_sub_u32_e32 v146, v141, v109
	v_min3_u32 v142, v142, v145, v146
	v_sub_u32_e32 v145, v141, v110
	v_sub_u32_e32 v146, v141, v111
	v_min3_u32 v142, v142, v145, v146
	v_sub_u32_e32 v145, v141, v112
	v_sub_u32_e32 v146, v141, v113
	v_min3_u32 v142, v142, v145, v146
	v_sub_u32_e32 v145, v141, v114
	v_sub_u32_e32 v146, v141, v115
	v_min3_u32 v142, v142, v145, v146
	v_sub_u32_e32 v145, v141, v116
	v_sub_u32_e32 v146, v141, v117
	v_min3_u32 v142, v142, v145, v146
	v_sub_u32_e32 v145, v141, v118
	v_sub_u32_e32 v146, v141, v119
	v_min3_u32 v142, v142, v145, v146
	v_sub_u32_e32 v145, v141, v120
	v_sub_u32_e32 v146, v141, v121
	v_min3_u32 v142, v142, v145, v146
	v_sub_u32_e32 v145, v141, v122
	v_sub_u32_e32 v146, v141, v123
	v_min3_u32 v142, v142, v145, v146
	v_sub_u32_e32 v145, v141, v124
	v_sub_u32_e32 v146, v141, v125
	v_min3_u32 v142, v142, v145, v146
	v_sub_u32_e32 v145, v141, v126
	v_sub_u32_e32 v146, v141, v127
	v_min3_u32 v142, v142, v145, v146
	v_sub_u32_e32 v145, v141, v128
	v_sub_u32_e32 v146, v141, v129
	v_min3_u32 v142, v142, v145, v146
	v_sub_u32_e32 v145, v141, v130
	v_sub_u32_e32 v146, v141, v131
	v_min3_u32 v142, v142, v145, v146
	v_sub_u32_e32 v145, v141, v132
	v_sub_u32_e32 v146, v141, v133
	v_min3_u32 v142, v142, v145, v146
	s_nop 1
	v_min_u32_dpp v142, v142, v142 quad_perm:[1,0,3,2] row_mask:0xf bank_mask:0xf
	s_nop 1
	v_min_u32_dpp v142, v142, v142 quad_perm:[2,3,0,1] row_mask:0xf bank_mask:0xf
	s_nop 1
	v_min_u32_dpp v142, v142, v142 row_half_mirror row_mask:0xf bank_mask:0xf
	v_sub_u32_e32 v143, v141, v142
	v_add_u32_e32 v141, -1, v143
	v_sub_u32_e32 v142, v141, v102
	v_sub_u32_e32 v145, v141, v103
	v_min_u32_e32 v142, v142, v145
	v_sub_u32_e32 v145, v141, v104
	v_sub_u32_e32 v146, v141, v105
	v_min3_u32 v142, v142, v145, v146
	v_sub_u32_e32 v145, v141, v106
	v_sub_u32_e32 v146, v141, v107
	v_min3_u32 v142, v142, v145, v146
	v_sub_u32_e32 v145, v141, v108
	v_sub_u32_e32 v146, v141, v109
	v_min3_u32 v142, v142, v145, v146
	v_sub_u32_e32 v145, v141, v110
	v_sub_u32_e32 v146, v141, v111
	v_min3_u32 v142, v142, v145, v146
	v_sub_u32_e32 v145, v141, v112
	v_sub_u32_e32 v146, v141, v113
	v_min3_u32 v142, v142, v145, v146
	v_sub_u32_e32 v145, v141, v114
	v_sub_u32_e32 v146, v141, v115
	v_min3_u32 v142, v142, v145, v146
	v_sub_u32_e32 v145, v141, v116
	v_sub_u32_e32 v146, v141, v117
	v_min3_u32 v142, v142, v145, v146
	v_sub_u32_e32 v145, v141, v118
	v_sub_u32_e32 v146, v141, v119
	v_min3_u32 v142, v142, v145, v146
	v_sub_u32_e32 v145, v141, v120
	v_sub_u32_e32 v146, v141, v121
	v_min3_u32 v142, v142, v145, v146
	v_sub_u32_e32 v145, v141, v122
	v_sub_u32_e32 v146, v141, v123
	v_min3_u32 v142, v142, v145, v146
	v_sub_u32_e32 v145, v141, v124
	v_sub_u32_e32 v146, v141, v125
	v_min3_u32 v142, v142, v145, v146
	v_sub_u32_e32 v145, v141, v126
	v_sub_u32_e32 v146, v141, v127
	v_min3_u32 v142, v142, v145, v146
	v_sub_u32_e32 v145, v141, v128
	v_sub_u32_e32 v146, v141, v129
	v_min3_u32 v142, v142, v145, v146
	v_sub_u32_e32 v145, v141, v130
	v_sub_u32_e32 v146, v141, v131
	v_min3_u32 v142, v142, v145, v146
	v_sub_u32_e32 v145, v141, v132
	v_sub_u32_e32 v146, v141, v133
	v_min3_u32 v142, v142, v145, v146
	s_nop 1
	v_min_u32_dpp v142, v142, v142 quad_perm:[1,0,3,2] row_mask:0xf bank_mask:0xf
	s_nop 1
	v_min_u32_dpp v142, v142, v142 quad_perm:[2,3,0,1] row_mask:0xf bank_mask:0xf
	s_nop 1
	v_min_u32_dpp v142, v142, v142 row_half_mirror row_mask:0xf bank_mask:0xf
	v_sub_u32_e32 v143, v141, v142
	v_add_u32_e32 v141, -1, v143
	v_sub_u32_e32 v142, v141, v102
	v_sub_u32_e32 v145, v141, v103
	v_min_u32_e32 v142, v142, v145
	v_sub_u32_e32 v145, v141, v104
	v_sub_u32_e32 v146, v141, v105
	v_min3_u32 v142, v142, v145, v146
	v_sub_u32_e32 v145, v141, v106
	v_sub_u32_e32 v146, v141, v107
	v_min3_u32 v142, v142, v145, v146
	v_sub_u32_e32 v145, v141, v108
	v_sub_u32_e32 v146, v141, v109
	v_min3_u32 v142, v142, v145, v146
	v_sub_u32_e32 v145, v141, v110
	v_sub_u32_e32 v146, v141, v111
	v_min3_u32 v142, v142, v145, v146
	v_sub_u32_e32 v145, v141, v112
	v_sub_u32_e32 v146, v141, v113
	v_min3_u32 v142, v142, v145, v146
	v_sub_u32_e32 v145, v141, v114
	v_sub_u32_e32 v146, v141, v115
	v_min3_u32 v142, v142, v145, v146
	v_sub_u32_e32 v145, v141, v116
	v_sub_u32_e32 v146, v141, v117
	v_min3_u32 v142, v142, v145, v146
	v_sub_u32_e32 v145, v141, v118
	v_sub_u32_e32 v146, v141, v119
	v_min3_u32 v142, v142, v145, v146
	v_sub_u32_e32 v145, v141, v120
	v_sub_u32_e32 v146, v141, v121
	v_min3_u32 v142, v142, v145, v146
	v_sub_u32_e32 v145, v141, v122
	v_sub_u32_e32 v146, v141, v123
	v_min3_u32 v142, v142, v145, v146
	v_sub_u32_e32 v145, v141, v124
	v_sub_u32_e32 v146, v141, v125
	v_min3_u32 v142, v142, v145, v146
	v_sub_u32_e32 v145, v141, v126
	v_sub_u32_e32 v146, v141, v127
	v_min3_u32 v142, v142, v145, v146
	v_sub_u32_e32 v145, v141, v128
	v_sub_u32_e32 v146, v141, v129
	v_min3_u32 v142, v142, v145, v146
	v_sub_u32_e32 v145, v141, v130
	v_sub_u32_e32 v146, v141, v131
	v_min3_u32 v142, v142, v145, v146
	v_sub_u32_e32 v145, v141, v132
	v_sub_u32_e32 v146, v141, v133
	v_min3_u32 v142, v142, v145, v146
	s_nop 1
	v_min_u32_dpp v142, v142, v142 quad_perm:[1,0,3,2] row_mask:0xf bank_mask:0xf
	s_nop 1
	v_min_u32_dpp v142, v142, v142 quad_perm:[2,3,0,1] row_mask:0xf bank_mask:0xf
	s_nop 1
	v_min_u32_dpp v142, v142, v142 row_half_mirror row_mask:0xf bank_mask:0xf
	v_sub_u32_e32 v143, v141, v142
	v_add_u32_e32 v141, -1, v143
	v_sub_u32_e32 v142, v141, v102
	v_sub_u32_e32 v145, v141, v103
	v_min_u32_e32 v142, v142, v145
	v_sub_u32_e32 v145, v141, v104
	v_sub_u32_e32 v146, v141, v105
	v_min3_u32 v142, v142, v145, v146
	v_sub_u32_e32 v145, v141, v106
	v_sub_u32_e32 v146, v141, v107
	v_min3_u32 v142, v142, v145, v146
	v_sub_u32_e32 v145, v141, v108
	v_sub_u32_e32 v146, v141, v109
	v_min3_u32 v142, v142, v145, v146
	v_sub_u32_e32 v145, v141, v110
	v_sub_u32_e32 v146, v141, v111
	v_min3_u32 v142, v142, v145, v146
	v_sub_u32_e32 v145, v141, v112
	v_sub_u32_e32 v146, v141, v113
	v_min3_u32 v142, v142, v145, v146
	v_sub_u32_e32 v145, v141, v114
	v_sub_u32_e32 v146, v141, v115
	v_min3_u32 v142, v142, v145, v146
	v_sub_u32_e32 v145, v141, v116
	v_sub_u32_e32 v146, v141, v117
	v_min3_u32 v142, v142, v145, v146
	v_sub_u32_e32 v145, v141, v118
	v_sub_u32_e32 v146, v141, v119
	v_min3_u32 v142, v142, v145, v146
	v_sub_u32_e32 v145, v141, v120
	v_sub_u32_e32 v146, v141, v121
	v_min3_u32 v142, v142, v145, v146
	v_sub_u32_e32 v145, v141, v122
	v_sub_u32_e32 v146, v141, v123
	v_min3_u32 v142, v142, v145, v146
	v_sub_u32_e32 v145, v141, v124
	v_sub_u32_e32 v146, v141, v125
	v_min3_u32 v142, v142, v145, v146
	v_sub_u32_e32 v145, v141, v126
	v_sub_u32_e32 v146, v141, v127
	v_min3_u32 v142, v142, v145, v146
	v_sub_u32_e32 v145, v141, v128
	v_sub_u32_e32 v146, v141, v129
	v_min3_u32 v142, v142, v145, v146
	v_sub_u32_e32 v145, v141, v130
	v_sub_u32_e32 v146, v141, v131
	v_min3_u32 v142, v142, v145, v146
	v_sub_u32_e32 v145, v141, v132
	v_sub_u32_e32 v146, v141, v133
	v_min3_u32 v142, v142, v145, v146
	s_nop 1
	v_min_u32_dpp v142, v142, v142 quad_perm:[1,0,3,2] row_mask:0xf bank_mask:0xf
	s_nop 1
	v_min_u32_dpp v142, v142, v142 quad_perm:[2,3,0,1] row_mask:0xf bank_mask:0xf
	s_nop 1
	v_min_u32_dpp v142, v142, v142 row_half_mirror row_mask:0xf bank_mask:0xf
	v_sub_u32_e32 v143, v141, v142
	v_add_u32_e32 v141, -1, v143
	v_mov_b32_e32 v144, 0
	v_cmp_ge_u32_e32 vcc, v102, v143
	v_addc_co_u32_e32 v144, vcc, 0, v144, vcc
	v_cmp_ge_u32_e32 vcc, v103, v143
	v_addc_co_u32_e32 v144, vcc, 0, v144, vcc
	v_cmp_ge_u32_e32 vcc, v104, v143
	v_addc_co_u32_e32 v144, vcc, 0, v144, vcc
	v_cmp_ge_u32_e32 vcc, v105, v143
	v_addc_co_u32_e32 v144, vcc, 0, v144, vcc
	v_cmp_ge_u32_e32 vcc, v106, v143
	v_addc_co_u32_e32 v144, vcc, 0, v144, vcc
	v_cmp_ge_u32_e32 vcc, v107, v143
	v_addc_co_u32_e32 v144, vcc, 0, v144, vcc
	v_cmp_ge_u32_e32 vcc, v108, v143
	v_addc_co_u32_e32 v144, vcc, 0, v144, vcc
	v_cmp_ge_u32_e32 vcc, v109, v143
	v_addc_co_u32_e32 v144, vcc, 0, v144, vcc
	v_cmp_ge_u32_e32 vcc, v110, v143
	v_addc_co_u32_e32 v144, vcc, 0, v144, vcc
	v_cmp_ge_u32_e32 vcc, v111, v143
	v_addc_co_u32_e32 v144, vcc, 0, v144, vcc
	v_cmp_ge_u32_e32 vcc, v112, v143
	v_addc_co_u32_e32 v144, vcc, 0, v144, vcc
	v_cmp_ge_u32_e32 vcc, v113, v143
	v_addc_co_u32_e32 v144, vcc, 0, v144, vcc
	v_cmp_ge_u32_e32 vcc, v114, v143
	v_addc_co_u32_e32 v144, vcc, 0, v144, vcc
	v_cmp_ge_u32_e32 vcc, v115, v143
	v_addc_co_u32_e32 v144, vcc, 0, v144, vcc
	v_cmp_ge_u32_e32 vcc, v116, v143
	v_addc_co_u32_e32 v144, vcc, 0, v144, vcc
	v_cmp_ge_u32_e32 vcc, v117, v143
	v_addc_co_u32_e32 v144, vcc, 0, v144, vcc
	v_cmp_ge_u32_e32 vcc, v118, v143
	v_addc_co_u32_e32 v144, vcc, 0, v144, vcc
	v_cmp_ge_u32_e32 vcc, v119, v143
	v_addc_co_u32_e32 v144, vcc, 0, v144, vcc
	v_cmp_ge_u32_e32 vcc, v120, v143
	v_addc_co_u32_e32 v144, vcc, 0, v144, vcc
	v_cmp_ge_u32_e32 vcc, v121, v143
	v_addc_co_u32_e32 v144, vcc, 0, v144, vcc
	v_cmp_ge_u32_e32 vcc, v122, v143
	v_addc_co_u32_e32 v144, vcc, 0, v144, vcc
	v_cmp_ge_u32_e32 vcc, v123, v143
	v_addc_co_u32_e32 v144, vcc, 0, v144, vcc
	v_cmp_ge_u32_e32 vcc, v124, v143
	v_addc_co_u32_e32 v144, vcc, 0, v144, vcc
	v_cmp_ge_u32_e32 vcc, v125, v143
	v_addc_co_u32_e32 v144, vcc, 0, v144, vcc
	v_cmp_ge_u32_e32 vcc, v126, v143
	v_addc_co_u32_e32 v144, vcc, 0, v144, vcc
	v_cmp_ge_u32_e32 vcc, v127, v143
	v_addc_co_u32_e32 v144, vcc, 0, v144, vcc
	v_cmp_ge_u32_e32 vcc, v128, v143
	v_addc_co_u32_e32 v144, vcc, 0, v144, vcc
	v_cmp_ge_u32_e32 vcc, v129, v143
	v_addc_co_u32_e32 v144, vcc, 0, v144, vcc
	v_cmp_ge_u32_e32 vcc, v130, v143
	v_addc_co_u32_e32 v144, vcc, 0, v144, vcc
	v_cmp_ge_u32_e32 vcc, v131, v143
	v_addc_co_u32_e32 v144, vcc, 0, v144, vcc
	v_cmp_ge_u32_e32 vcc, v132, v143
	v_addc_co_u32_e32 v144, vcc, 0, v144, vcc
	v_cmp_ge_u32_e32 vcc, v133, v143
	v_addc_co_u32_e32 v144, vcc, 0, v144, vcc
	s_nop 1
	v_add_u32_dpp v144, v144, v144 quad_perm:[1,0,3,2] row_mask:0xf bank_mask:0xf
	s_nop 1
	v_add_u32_dpp v144, v144, v144 quad_perm:[2,3,0,1] row_mask:0xf bank_mask:0xf
	s_nop 1
	v_add_u32_dpp v144, v144, v144 row_half_mirror row_mask:0xf bank_mask:0xf
	v_cmp_ne_u32_e32 vcc, 13, v144
	s_cmp_lg_u64 vcc, 0
	s_cbranch_scc1 .Ltk8_slow
	v_cmp_ge_u32_e32 vcc, v102, v143
	s_and_saveexec_b64 s[14:15], vcc
	ds_or_b32 v139, v140
	s_mov_b64 exec, s[14:15]
	v_cmp_ge_u32_e32 vcc, v103, v143
	s_and_saveexec_b64 s[14:15], vcc
	ds_or_b32 v139, v140 offset:8
	s_mov_b64 exec, s[14:15]
	v_cmp_ge_u32_e32 vcc, v104, v143
	s_and_saveexec_b64 s[14:15], vcc
	ds_or_b32 v139, v140 offset:16
	s_mov_b64 exec, s[14:15]
	v_cmp_ge_u32_e32 vcc, v105, v143
	s_and_saveexec_b64 s[14:15], vcc
	ds_or_b32 v139, v140 offset:24
	s_mov_b64 exec, s[14:15]
	v_cmp_ge_u32_e32 vcc, v106, v143
	s_and_saveexec_b64 s[14:15], vcc
	ds_or_b32 v139, v140 offset:32
	s_mov_b64 exec, s[14:15]
	v_cmp_ge_u32_e32 vcc, v107, v143
	s_and_saveexec_b64 s[14:15], vcc
	ds_or_b32 v139, v140 offset:40
	s_mov_b64 exec, s[14:15]
	v_cmp_ge_u32_e32 vcc, v108, v143
	s_and_saveexec_b64 s[14:15], vcc
	ds_or_b32 v139, v140 offset:48
	s_mov_b64 exec, s[14:15]
	v_cmp_ge_u32_e32 vcc, v109, v143
	s_and_saveexec_b64 s[14:15], vcc
	ds_or_b32 v139, v140 offset:56
	s_mov_b64 exec, s[14:15]
	v_cmp_ge_u32_e32 vcc, v110, v143
	s_and_saveexec_b64 s[14:15], vcc
	ds_or_b32 v139, v140 offset:64
	s_mov_b64 exec, s[14:15]
	v_cmp_ge_u32_e32 vcc, v111, v143
	s_and_saveexec_b64 s[14:15], vcc
	ds_or_b32 v139, v140 offset:72
	s_mov_b64 exec, s[14:15]
	v_cmp_ge_u32_e32 vcc, v112, v143
	s_and_saveexec_b64 s[14:15], vcc
	ds_or_b32 v139, v140 offset:80
	s_mov_b64 exec, s[14:15]
	v_cmp_ge_u32_e32 vcc, v113, v143
	s_and_saveexec_b64 s[14:15], vcc
	ds_or_b32 v139, v140 offset:88
	s_mov_b64 exec, s[14:15]
	v_cmp_ge_u32_e32 vcc, v114, v143
	s_and_saveexec_b64 s[14:15], vcc
	ds_or_b32 v139, v140 offset:96
	s_mov_b64 exec, s[14:15]
	v_cmp_ge_u32_e32 vcc, v115, v143
	s_and_saveexec_b64 s[14:15], vcc
	ds_or_b32 v139, v140 offset:104
	s_mov_b64 exec, s[14:15]
	v_cmp_ge_u32_e32 vcc, v116, v143
	s_and_saveexec_b64 s[14:15], vcc
	ds_or_b32 v139, v140 offset:112
	s_mov_b64 exec, s[14:15]
	v_cmp_ge_u32_e32 vcc, v117, v143
	s_and_saveexec_b64 s[14:15], vcc
	ds_or_b32 v139, v140 offset:120
	s_mov_b64 exec, s[14:15]
	v_cmp_ge_u32_e32 vcc, v118, v143
	s_and_saveexec_b64 s[14:15], vcc
	ds_or_b32 v139, v140 offset:128
	s_mov_b64 exec, s[14:15]
	v_cmp_ge_u32_e32 vcc, v119, v143
	s_and_saveexec_b64 s[14:15], vcc
	ds_or_b32 v139, v140 offset:136
	s_mov_b64 exec, s[14:15]
	v_cmp_ge_u32_e32 vcc, v120, v143
	s_and_saveexec_b64 s[14:15], vcc
	ds_or_b32 v139, v140 offset:144
	s_mov_b64 exec, s[14:15]
	v_cmp_ge_u32_e32 vcc, v121, v143
	s_and_saveexec_b64 s[14:15], vcc
	ds_or_b32 v139, v140 offset:152
	s_mov_b64 exec, s[14:15]
	v_cmp_ge_u32_e32 vcc, v122, v143
	s_and_saveexec_b64 s[14:15], vcc
	ds_or_b32 v139, v140 offset:160
	s_mov_b64 exec, s[14:15]
	v_cmp_ge_u32_e32 vcc, v123, v143
	s_and_saveexec_b64 s[14:15], vcc
	ds_or_b32 v139, v140 offset:168
	s_mov_b64 exec, s[14:15]
	v_cmp_ge_u32_e32 vcc, v124, v143
	s_and_saveexec_b64 s[14:15], vcc
	ds_or_b32 v139, v140 offset:176
	s_mov_b64 exec, s[14:15]
	v_cmp_ge_u32_e32 vcc, v125, v143
	s_and_saveexec_b64 s[14:15], vcc
	ds_or_b32 v139, v140 offset:184
	s_mov_b64 exec, s[14:15]
	v_cmp_ge_u32_e32 vcc, v126, v143
	s_and_saveexec_b64 s[14:15], vcc
	ds_or_b32 v139, v140 offset:192
	s_mov_b64 exec, s[14:15]
	v_cmp_ge_u32_e32 vcc, v127, v143
	s_and_saveexec_b64 s[14:15], vcc
	ds_or_b32 v139, v140 offset:200
	s_mov_b64 exec, s[14:15]
	v_cmp_ge_u32_e32 vcc, v128, v143
	s_and_saveexec_b64 s[14:15], vcc
	ds_or_b32 v139, v140 offset:208
	s_mov_b64 exec, s[14:15]
	v_cmp_ge_u32_e32 vcc, v129, v143
	s_and_saveexec_b64 s[14:15], vcc
	ds_or_b32 v139, v140 offset:216
	s_mov_b64 exec, s[14:15]
	v_cmp_ge_u32_e32 vcc, v130, v143
	s_and_saveexec_b64 s[14:15], vcc
	ds_or_b32 v139, v140 offset:224
	s_mov_b64 exec, s[14:15]
	v_cmp_ge_u32_e32 vcc, v131, v143
	s_and_saveexec_b64 s[14:15], vcc
	ds_or_b32 v139, v140 offset:232
	s_mov_b64 exec, s[14:15]
	v_cmp_ge_u32_e32 vcc, v132, v143
	s_and_saveexec_b64 s[14:15], vcc
	ds_or_b32 v139, v140 offset:240
	s_mov_b64 exec, s[14:15]
	v_cmp_ge_u32_e32 vcc, v133, v143
	s_and_saveexec_b64 s[14:15], vcc
	ds_or_b32 v139, v140 offset:248
	s_mov_b64 exec, s[14:15]
	s_branch .LBB0_1296
.Ltk8_slow:
	s_lshl_b32 s0, s53, 6
	s_add_i32 s1, s53, -2
	v_cmp_lt_i32_e32 vcc, s1, v223
	s_add_i32 s18, s34, s0
	s_or_b64 s[30:31], s[4:5], vcc
	v_cmp_gt_i32_e32 vcc, s1, v223
	v_cmp_lt_i32_e64 s[8:9], s1, v224
	v_cmp_lt_i32_e64 s[10:11], s1, v225
	s_lshl_b64 s[0:1], s[18:19], 11
	s_bitcmp1_b32 s12, 0
	s_cselect_b64 s[12:13], -1, 0
	s_xor_b64 s[12:13], s[12:13], -1
	v_cndmask_b32_e64 v2, 0, 1, s[12:13]
	v_lshlrev_b32_e32 v2, 10, v2
	s_waitcnt vmcnt(47)
	v_or_b32_e32 v4, s0, v2
	v_mov_b32_e32 v5, s1
	v_lshl_add_u64 v[4:5], v[208:209], 0, v[4:5]
	s_mov_b32 s18, 0
	global_load_dwordx4 v[12:15], v[4:5], off
	s_branch .LBB0_1270

.LBB0_1317:
	v_ashrrev_i32_e32 v219, 31, v218
	v_ashrrev_i32_e32 v215, 31, v214
	s_lshl_b32 s1, s10, 21
	s_add_u32 s8, s36, s1
	s_addc_u32 s9, s37, 0
	s_add_u32 s11, s40, s1
	s_addc_u32 s12, s41, 0
	s_movk_i32 s82, 0x660
	s_waitcnt vmcnt(0)
	v_lshlrev_b32_e32 v2, 4, v199
	v_mov_b32_e32 v22, v218
	v_mov_b32_e32 v23, v4
	v_mov_b32_e32 v24, v9
	v_mov_b32_e32 v25, v10
	v_and_b32_e32 v18, 7, v226
	v_lshlrev_b32_e32 v18, 3, v18
	v_mov_b32_e32 v19, 0x110
	v_mul_u32_u24_e32 v19, v19, v200
	v_lshl_add_u32 v19, v206, 2, v19
	v_add_u32_e32 v19, 0x4000, v19
	v_lshl_add_u32 v20, v216, 1, v210
	v_mov_b32_e32 v31, 0x110
	v_mul_u32_u24_e32 v31, v31, v200
	v_add_u32_e32 v31, 0x4100, v31
	v_add_u32_e32 v31, v31, v206
	v_mov_b32_e32 v82, 0
	v_mov_b32_e32 v83, 0
	v_mov_b32_e32 v84, 0
	v_mov_b32_e32 v85, 0
	s_lshl_b32 s0, s77, 10
	s_add_i32 s0, s0, 0x4000
	v_add_u32_e32 v28, s0, v2
	v_add_u32_e32 v29, 0x10000, v28
	ds_write_b128 v28, v[82:85]
	ds_write_b128 v28, v[82:85] offset:8192
	ds_write_b128 v28, v[82:85] offset:16384
	ds_write_b128 v28, v[82:85] offset:24576
	ds_write_b128 v28, v[82:85] offset:32768
	ds_write_b128 v28, v[82:85] offset:40960
	ds_write_b128 v28, v[82:85] offset:49152
	ds_write_b128 v28, v[82:85] offset:57344
	ds_write_b128 v29, v[82:85]
	ds_write_b128 v29, v[82:85] offset:8192
	ds_write_b128 v29, v[82:85] offset:16384
	ds_write_b128 v29, v[82:85] offset:24576
	ds_write_b128 v29, v[82:85] offset:32768
	v_mov_b32_e32 v86, 0x1800
	ds_write_b32 v86, v82
	ds_write_b64 v86, v[82:83] offset:8
	s_lshl_b32 s90, s77, 8
	s_add_i32 s90, s90, 0x1e000
	v_lshl_add_u32 v122, v199, 2, s90
	ds_write_b32 v122, v82
	s_waitcnt lgkmcnt(0)
	s_barrier
	v_and_b32_e32 v102, 31, v199
	s_lshl_b32 s0, s77, 5
	v_add_u32_e32 v103, s0, v102
	s_mov_b64 s[58:59], exec
	v_cmp_gt_u32_e32 vcc, 32, v199
	s_and_b64 exec, exec, vcc
	v_lshlrev_b32_e32 v106, 3, v103
	ds_read_b64 v[104:105], v106
	s_waitcnt lgkmcnt(0)
	v_bcnt_u32_b32 v107, v104, 0
	v_bcnt_u32_b32 v107, v105, v107
	v_add_u32_e32 v108, 3, v107
	v_lshrrev_b32_e32 v108, 2, v108
	v_cmp_eq_u32_e64 s[92:93], 64, v107
	v_cndmask_b32_e64 v107, v107, 0, s[92:93]
	v_mov_b32_e32 v110, 0x1800
	ds_add_rtn_u32 v109, v110, v108
	s_waitcnt lgkmcnt(0)

.Lq_full:
	s_cmp_eq_u64 s[92:93], 0
	s_cbranch_scc1 .Lq_full_done
	s_ff1_i32_b64 s0, s[92:93]
	s_bitset0_b64 s[92:93], s0
	s_nop 3
	v_readlane_b32 s1, v103, s0
	v_readlane_b32 s14, v109, s0
	s_or_b32 s1, s1, 0x400
	v_mov_b32_e32 v120, s1
	v_mov_b32_e32 v121, 0x04040404
	v_mul_lo_u32 v121, v121, v199
	v_add_u32_e32 v121, 0x03020100, v121
	v_add_lshl_u32 v122, v199, s14, 3
	v_cmp_gt_u32_e32 vcc, 16, v199
	s_and_b64 exec, exec, vcc
	ds_write_b64 v122, v[120:121] offset:2048
	s_mov_b64 exec, s[58:59]
	s_branch .Lq_full
.Lq_full_done:
	s_waitcnt lgkmcnt(0)
	s_barrier
	v_mov_b32_e32 v110, 0x1800
	ds_read_b32 v111, v110
	s_waitcnt lgkmcnt(0)
	v_readfirstlane_b32 s0, v111
	s_mul_i32 s1, s0, s77
	s_lshr_b32 s1, s1, 3
	s_add_i32 s14, s77, 1
	s_mul_i32 s14, s0, s14
	s_lshr_b32 s14, s14, 3
	s_sub_i32 s10, s14, s1
	v_cmp_gt_u32_e32 vcc, s10, v199
	v_mov_b32_e32 v26, 0
	v_mov_b32_e32 v27, 0
	v_add_u32_e32 v112, s1, v199
	v_lshlrev_b32_e32 v113, 3, v112
	s_and_b64 exec, exec, vcc
	ds_read_b64 v[114:115], v113 offset:2048
	s_waitcnt lgkmcnt(0)
	v_mov_b32_e32 v26, v114
	v_mov_b32_e32 v27, v115
	s_mov_b64 exec, s[58:59]
	v_and_b32_e32 v116, 0xff, v26
	v_add_u32_e32 v117, -1, v199
	v_lshlrev_b32_e32 v117, 2, v117
	ds_bpermute_b32 v118, v117, v116
	s_waitcnt lgkmcnt(0)
	v_cmp_ne_u32_e64 s[14:15], v116, v118
	v_cmp_eq_u32_e64 s[30:31], 0, v199
	s_or_b64 s[14:15], s[14:15], s[30:31]
	s_and_b64 s[14:15], s[14:15], vcc
	s_bcnt1_i32_b64 s89, s[14:15]
	v_mbcnt_lo_u32_b32 v119, s14, 0
	v_mbcnt_hi_u32_b32 v119, s15, v119
	v_lshl_or_b32 v120, v199, 8, v116
	v_lshl_add_u32 v121, v119, 2, s90
	s_mov_b64 exec, s[14:15]
	ds_write_b32 v121, v120
	s_mov_b64 exec, s[58:59]
	s_waitcnt lgkmcnt(0)
	v_lshl_add_u32 v122, v199, 2, s90
	ds_read_b32 v33, v122
	s_waitcnt lgkmcnt(0)
	s_mov_b32 s83, 0
.Lq_again:
	s_mov_b32 s52, 0
	s_mov_b32 s69, 0
	s_min_u32 s14, s69, 63
	s_nop 3
	v_readlane_b32 s30, v33, s14
	s_and_b32 s30, s30, 0xff
	s_lshl_b32 s30, s30, 13
	s_add_u32 s64, s11, s30
	s_addc_u32 s65, s12, 0
	s_add_u32 s66, s8, s30
	s_addc_u32 s67, s9, 0
	global_load_dwordx4 v[178:181], v2, s[64:65]
	global_load_dwordx4 v[174:177], v2, s[64:65] offset:1024
	global_load_dwordx4 v[170:173], v2, s[64:65] offset:2048
	global_load_dwordx4 v[166:169], v2, s[64:65] offset:3072
	global_load_dwordx4 v[146:149], v2, s[66:67]
	global_load_dwordx4 v[142:145], v2, s[66:67] offset:1024
	global_load_dwordx4 v[126:129], v2, s[66:67] offset:2048
	global_load_dwordx4 v[114:117], v2, s[66:67] offset:3072
	s_mov_b32 s69, 0
	s_min_u32 s14, s69, 63
	s_nop 3
	v_readlane_b32 s30, v26, s14
	v_readlane_b32 s31, v27, s14
	v_bfe_u32 v28, s31, v18, 8
	v_lshl_add_u32 v29, s99, 6, v28
	v_mad_u32_u24 v29, v29, s47, v20
	global_load_dwordx4 v[238:241], v29, s[20:21]
	global_load_dwordx4 v[242:245], v29, s[20:21] offset:32
	global_load_dwordx4 v[246:249], v29, s[20:21] offset:64
	global_load_dwordx4 v[250:253], v29, s[20:21] offset:96
	s_mov_b32 s69, 0
	s_min_u32 s14, s69, 63
	s_nop 3
	v_readlane_b32 s30, v33, s14
	s_and_b32 s30, s30, 0xff
	s_lshl_b32 s30, s30, 13
	s_or_b32 s30, s30, 0x1000
	s_add_u32 s64, s11, s30
	s_addc_u32 s65, s12, 0
	s_add_u32 s66, s8, s30
	s_addc_u32 s67, s9, 0
	global_load_dwordx4 v[162:165], v2, s[64:65]
	global_load_dwordx4 v[154:157], v2, s[64:65] offset:1024
	global_load_dwordx4 v[150:153], v2, s[64:65] offset:2048
	global_load_dwordx4 v[158:161], v2, s[64:65] offset:3072
	global_load_dwordx4 v[138:141], v2, s[66:67]
	global_load_dwordx4 v[122:125], v2, s[66:67] offset:1024
	global_load_dwordx4 v[110:113], v2, s[66:67] offset:2048
	global_load_dwordx4 v[106:109], v2, s[66:67] offset:3072
	s_mov_b32 s69, 1
	s_min_u32 s14, s69, 63
	s_nop 3
	v_readlane_b32 s30, v33, s14
	s_and_b32 s30, s30, 0xff
	s_lshl_b32 s30, s30, 13
	s_add_u32 s64, s11, s30
	s_addc_u32 s65, s12, 0
	s_add_u32 s66, s8, s30
	s_addc_u32 s67, s9, 0
	global_load_dwordx4 v[194:197], v2, s[64:65]
	global_load_dwordx4 v[190:193], v2, s[64:65] offset:1024
	global_load_dwordx4 v[186:189], v2, s[64:65] offset:2048
	global_load_dwordx4 v[182:185], v2, s[64:65] offset:3072
	global_load_dwordx4 v[134:137], v2, s[66:67]
	global_load_dwordx4 v[130:133], v2, s[66:67] offset:1024
	global_load_dwordx4 v[118:121], v2, s[66:67] offset:2048
	global_load_dwordx4 v[102:105], v2, s[66:67] offset:3072

.Lq_loop_end:
	s_waitcnt vmcnt(0) lgkmcnt(0)
	s_cmp_eq_u32 s83, 0
	s_cbranch_scc1 .Lq_norepeat
	s_add_i32 s83, s83, -1
	s_branch .Lq_again
.Lq_norepeat:
	s_barrier
	v_mov_b32_e32 v82, v22
	v_mov_b32_e32 v83, v23
	v_mov_b32_e32 v84, v24
	v_mov_b32_e32 v85, v25
	v_mad_u32_u24 v86, v226, s82, v19
	v_add_u32_e32 v87, 0x1980, v86
	v_mad_u32_u24 v88, v226, s82, v31
	v_add_u32_e32 v89, 0x1980, v88
	ds_read_b32 v66, v86
	ds_read_b32 v67, v86 offset:4
	ds_read_b32 v68, v86 offset:8
	ds_read_b32 v69, v86 offset:12
	ds_read_b32 v70, v86 offset:32
	ds_read_b32 v71, v86 offset:36
	ds_read_b32 v72, v86 offset:40
	ds_read_b32 v73, v86 offset:44
	ds_read_b32 v74, v86 offset:64
	ds_read_b32 v75, v86 offset:68
	ds_read_b32 v76, v86 offset:72
	ds_read_b32 v77, v86 offset:76
	ds_read_b32 v78, v86 offset:96
	ds_read_b32 v79, v86 offset:100
	ds_read_b32 v80, v86 offset:104
	ds_read_b32 v81, v86 offset:108
	ds_read_b32 v50, v86 offset:128
	ds_read_b32 v51, v86 offset:132
	ds_read_b32 v52, v86 offset:136
	ds_read_b32 v53, v86 offset:140
	ds_read_b32 v54, v86 offset:160
	ds_read_b32 v55, v86 offset:164
	ds_read_b32 v56, v86 offset:168
	ds_read_b32 v57, v86 offset:172
	ds_read_b32 v58, v86 offset:192
	ds_read_b32 v59, v86 offset:196
	ds_read_b32 v60, v86 offset:200
	ds_read_b32 v61, v86 offset:204
	ds_read_b32 v62, v86 offset:224
	ds_read_b32 v63, v86 offset:228
	ds_read_b32 v64, v86 offset:232
	ds_read_b32 v65, v86 offset:236
	ds_read_b32 v221, v88
	ds_read_b32 v34, v87
	ds_read_b32 v35, v87 offset:4
	ds_read_b32 v36, v87 offset:8
	ds_read_b32 v37, v87 offset:12
	ds_read_b32 v38, v87 offset:32
	ds_read_b32 v39, v87 offset:36
	ds_read_b32 v40, v87 offset:40
	ds_read_b32 v41, v87 offset:44
	ds_read_b32 v42, v87 offset:64
	ds_read_b32 v43, v87 offset:68
	ds_read_b32 v44, v87 offset:72
	ds_read_b32 v45, v87 offset:76
	ds_read_b32 v46, v87 offset:96
	ds_read_b32 v47, v87 offset:100
	ds_read_b32 v48, v87 offset:104
	ds_read_b32 v49, v87 offset:108
	ds_read_b32 v18, v87 offset:128
	ds_read_b32 v19, v87 offset:132
	ds_read_b32 v20, v87 offset:136
	ds_read_b32 v21, v87 offset:140
	ds_read_b32 v22, v87 offset:160
	ds_read_b32 v23, v87 offset:164
	ds_read_b32 v24, v87 offset:168
	ds_read_b32 v25, v87 offset:172
	ds_read_b32 v26, v87 offset:192
	ds_read_b32 v27, v87 offset:196
	ds_read_b32 v28, v87 offset:200
	ds_read_b32 v29, v87 offset:204
	ds_read_b32 v30, v87 offset:224
	ds_read_b32 v31, v87 offset:228
	ds_read_b32 v32, v87 offset:232
	ds_read_b32 v33, v87 offset:236
	ds_read_b32 v211, v89
	s_waitcnt lgkmcnt(0)
	v_mov_b32_e32 v218, v82
	v_mov_b32_e32 v4, v83
	v_mov_b32_e32 v9, v84
	v_mov_b32_e32 v10, v85
